# P2: hand-written store epilogue (permlane16_swap pairs -> dwordx4 stores, half the store instructions), all LDS-DMA before the epilogue, epilogue stores drain under next k-tile (vmcnt 16)
# speedup vs baseline: 1.0511x; 1.0301x over previous
.LBB0_164:
	s_mul_i32 s0, s24, 0x3c00000
	s_add_u32 s11, s30, s0
	v_readlane_b32 s0, v253, 61
	v_readlane_b32 s1, v253, 62
	s_addc_u32 s21, s31, 0
	s_andn2_b64 vcc, exec, s[0:1]
	s_cbranch_vccnz .LBB0_440
	v_mov_b32_e32 v0, v196
	s_mov_b32 s0, 0xffff0
	v_ashrrev_i32_e32 v2, 6, v0
	v_lshlrev_b32_e32 v5, 4, v0
	v_and_b32_e32 v6, 32, v0
	s_waitcnt vmcnt(20)
	v_bfe_u32 v7, v0, 2, 4
	v_bitop3_b32 v5, v5, v6, 48 bitop3:0x6c
	v_lshlrev_b32_e32 v6, 3, v2
	v_lshlrev_b32_e32 v4, 10, v2
	v_and_or_b32 v5, v0, 64, v5
	v_and_or_b32 v6, v6, s0, v7
	v_lshl_or_b32 v130, v6, 12, v5
	v_add_u32_e32 v6, 0x2000, v4
	v_lshrrev_b32_e32 v6, 7, v6
	v_and_or_b32 v6, v6, s0, v7
	v_lshl_or_b32 v132, v6, 12, v5
	v_add_u32_e32 v6, 0x4000, v4
	v_lshrrev_b32_e32 v6, 7, v6
	v_and_or_b32 v6, v6, s0, v7
	v_lshl_or_b32 v134, v6, 12, v5
	v_add_u32_e32 v6, 0x6000, v4
	v_lshrrev_b32_e32 v6, 7, v6
	v_and_b32_e32 v138, 0x1c00, v4
	v_and_or_b32 v6, v6, s0, v7
	v_readfirstlane_b32 s0, v138
	v_readlane_b32 s12, v253, 8
	v_or_b32_e32 v139, 0x2000, v138
	s_mov_b32 m0, s0
	v_readlane_b32 s13, v253, 9
	v_readfirstlane_b32 s0, v139
	v_or_b32_e32 v140, 0x4000, v138
	s_barrier
	s_nop 1
	global_load_lds_dwordx4 v130, s[12:13]
	s_mov_b32 m0, s0
	v_readfirstlane_b32 s0, v140
	v_or_b32_e32 v141, 0x6000, v138
	global_load_lds_dwordx4 v132, s[12:13]
	s_mov_b32 m0, s0
	v_readfirstlane_b32 s0, v141
	global_load_lds_dwordx4 v134, s[12:13]
	s_mov_b32 m0, s0
	v_readlane_b32 s0, v253, 6
	v_or_b32_e32 v142, 0x8000, v138
	v_lshl_or_b32 v136, v6, 12, v5
	v_readlane_b32 s1, v253, 7
	s_add_u32 s0, s11, s0
	v_readfirstlane_b32 s2, v142
	v_or_b32_e32 v143, 0xa000, v138
	global_load_lds_dwordx4 v136, s[12:13]
	s_addc_u32 s1, s21, s1
	s_mov_b32 m0, s2
	v_readfirstlane_b32 s2, v143
	v_or_b32_e32 v144, 0xc000, v138
	global_load_lds_dwordx4 v130, s[0:1]
	s_mov_b32 m0, s2
	v_readfirstlane_b32 s2, v144
	v_or_b32_e32 v145, 0xe000, v138
	global_load_lds_dwordx4 v132, s[0:1]
	s_mov_b32 m0, s2
	v_readfirstlane_b32 s2, v145
	global_load_lds_dwordx4 v134, s[0:1]
	s_mov_b32 m0, s2
	v_and_b32_e32 v3, 15, v0
	global_load_lds_dwordx4 v136, s[0:1]
	v_and_b32_e32 v4, 48, v0
	v_lshlrev_b32_e32 v3, 6, v3
	v_lshlrev_b32_e32 v6, 2, v0
	v_or_b32_e32 v5, v3, v4
	v_and_b32_e32 v6, 32, v6
	s_mov_b32 s2, 0x18000
	v_bitop3_b32 v146, v3, v6, v4 bitop3:0x36
	v_bitop3_b32 v3, v5, s2, v6 bitop3:0xde
	v_lshlrev_b32_e32 v0, 6, v0
	s_movk_i32 s2, 0x4800
	v_bitop3_b32 v157, v0, s2, v210 bitop3:0xc8
	s_waitcnt vmcnt(0)
	v_and_b32_e32 v8, 0x3c0, v0
	s_movk_i32 s2, 0x5800
	v_bitop3_b32 v158, v8, v6, v4 bitop3:0x36
	v_bitop3_b32 v10, v0, s2, v250 bitop3:0xc8
	v_mov_b32_e32 v11, 0x2000
	s_movk_i32 s2, 0x6800
	v_mov_b32_e32 v12, 0x2800
	v_mov_b32_e32 v13, 0x3000
	v_or_b32_e32 v4, v8, v4
	v_mov_b32_e32 v8, 0x3800
	s_waitcnt vmcnt(0)
	v_and_b32_e32 v7, 0x4000, v0
	v_bitop3_b32 v9, v0, s87, v211 bitop3:0xc8
	v_bitop3_b32 v11, v0, s36, v11 bitop3:0xc8
	v_bitop3_b32 v12, v0, s2, v12 bitop3:0xc8
	v_bitop3_b32 v13, v0, s52, v13 bitop3:0xc8
	v_bitop3_b32 v159, v0, s90, v8 bitop3:0xc8
	v_lshlrev_b32_e32 v0, 13, v2
	s_mov_b32 s2, 0x10000
	v_and_b32_e32 v160, 0x6000, v0
	v_bitop3_b32 v0, v5, s2, v6 bitop3:0xde
	v_bitop3_b32 v161, v4, s2, v6 bitop3:0xde
	v_mov_b32_e32 v126, 0
	v_mov_b32_e32 v131, v1
	v_mov_b32_e32 v133, v1
	v_mov_b32_e32 v135, v1
	v_mov_b32_e32 v137, v1
	v_or_b32_e32 v147, 0x10000, v138
	v_or_b32_e32 v148, 0x18000, v138
	v_or_b32_e32 v149, 0x12000, v138
	v_or_b32_e32 v152, 0x14000, v138
	v_or_b32_e32 v153, 0x16000, v138
	v_or_b32_e32 v154, 0x1a000, v138
	v_or_b32_e32 v155, 0x1c000, v138
	v_or_b32_e32 v156, 0x1e000, v138
	s_mov_b32 s45, 1
	s_mov_b32 s22, 0
	v_add_u32_e32 v162, v146, v7
	v_add_u32_e32 v163, v158, v157
	v_add_u32_e32 v164, v158, v9
	v_add_u32_e32 v165, v158, v10
	v_add_u32_e32 v166, v158, v11
	v_add_u32_e32 v167, v158, v12
	v_add_u32_e32 v168, v158, v13
	v_add_u32_e32 v169, v0, v7
	v_add_u32_e32 v170, v161, v9
	v_add_u32_e32 v171, v161, v10
	v_add_u32_e32 v172, v161, v11
	v_add_u32_e32 v173, v161, v12
	v_add_u32_e32 v174, v161, v13
	v_add_u32_e32 v175, v161, v159
	v_add_u32_e32 v176, v3, v160
	s_mov_b32 s44, 0
	s_mov_b32 s6, 0
	s_mov_b32 s46, 0
	s_mov_b64 s[2:3], s[12:13]
	v_mov_b32_e32 v127, v126
	v_mov_b32_e32 v128, v126
	v_mov_b32_e32 v129, v126
	v_mov_b32_e32 v122, v126
	v_mov_b32_e32 v123, v126
	v_mov_b32_e32 v124, v126
	v_mov_b32_e32 v125, v126
	v_mov_b32_e32 v118, v126
	v_mov_b32_e32 v119, v126
	v_mov_b32_e32 v120, v126
	v_mov_b32_e32 v121, v126
	v_mov_b32_e32 v114, v126
	v_mov_b32_e32 v115, v126
	v_mov_b32_e32 v116, v126
	v_mov_b32_e32 v117, v126
	v_mov_b32_e32 v110, v126
	v_mov_b32_e32 v111, v126
	v_mov_b32_e32 v112, v126
	v_mov_b32_e32 v113, v126
	v_mov_b32_e32 v106, v126
	v_mov_b32_e32 v107, v126
	v_mov_b32_e32 v108, v126
	v_mov_b32_e32 v109, v126
	v_mov_b32_e32 v102, v126
	v_mov_b32_e32 v103, v126
	v_mov_b32_e32 v104, v126
	v_mov_b32_e32 v105, v126
	v_mov_b32_e32 v98, v126
	v_mov_b32_e32 v99, v126
	v_mov_b32_e32 v100, v126
	v_mov_b32_e32 v101, v126
	v_mov_b32_e32 v94, v126
	v_mov_b32_e32 v95, v126
	v_mov_b32_e32 v96, v126
	v_mov_b32_e32 v97, v126
	v_mov_b32_e32 v90, v126
	v_mov_b32_e32 v91, v126
	v_mov_b32_e32 v92, v126
	v_mov_b32_e32 v93, v126
	v_mov_b32_e32 v86, v126
	v_mov_b32_e32 v87, v126
	v_mov_b32_e32 v88, v126
	v_mov_b32_e32 v89, v126
	v_mov_b32_e32 v82, v126
	v_mov_b32_e32 v83, v126
	v_mov_b32_e32 v84, v126
	v_mov_b32_e32 v85, v126
	v_mov_b32_e32 v78, v126
	v_mov_b32_e32 v79, v126
	v_mov_b32_e32 v80, v126
	v_mov_b32_e32 v81, v126
	v_mov_b32_e32 v74, v126
	v_mov_b32_e32 v75, v126
	v_mov_b32_e32 v76, v126
	v_mov_b32_e32 v77, v126
	v_mov_b32_e32 v70, v126
	v_mov_b32_e32 v71, v126
	v_mov_b32_e32 v72, v126
	v_mov_b32_e32 v73, v126
	v_mov_b32_e32 v66, v126
	v_mov_b32_e32 v67, v126
	v_mov_b32_e32 v68, v126
	v_mov_b32_e32 v69, v126
	v_mov_b32_e32 v62, v126
	v_mov_b32_e32 v63, v126
	v_mov_b32_e32 v64, v126
	v_mov_b32_e32 v65, v126
	v_mov_b32_e32 v58, v126
	v_mov_b32_e32 v59, v126
	v_mov_b32_e32 v60, v126
	v_mov_b32_e32 v61, v126
	v_mov_b32_e32 v54, v126
	v_mov_b32_e32 v55, v126
	v_mov_b32_e32 v56, v126
	v_mov_b32_e32 v57, v126
	v_mov_b32_e32 v50, v126
	v_mov_b32_e32 v51, v126
	v_mov_b32_e32 v52, v126
	v_mov_b32_e32 v53, v126
	v_mov_b32_e32 v46, v126
	v_mov_b32_e32 v47, v126
	v_mov_b32_e32 v48, v126
	v_mov_b32_e32 v49, v126
	v_mov_b32_e32 v42, v126
	v_mov_b32_e32 v43, v126
	v_mov_b32_e32 v44, v126
	v_mov_b32_e32 v45, v126
	v_mov_b32_e32 v38, v126
	v_mov_b32_e32 v39, v126
	v_mov_b32_e32 v40, v126
	v_mov_b32_e32 v41, v126
	v_mov_b32_e32 v34, v126
	v_mov_b32_e32 v35, v126
	v_mov_b32_e32 v36, v126
	v_mov_b32_e32 v37, v126
	v_mov_b32_e32 v30, v126
	v_mov_b32_e32 v31, v126
	v_mov_b32_e32 v32, v126
	v_mov_b32_e32 v33, v126
	v_mov_b32_e32 v26, v126
	v_mov_b32_e32 v27, v126
	v_mov_b32_e32 v28, v126
	v_mov_b32_e32 v29, v126
	v_mov_b32_e32 v22, v126
	v_mov_b32_e32 v23, v126
	v_mov_b32_e32 v24, v126
	v_mov_b32_e32 v25, v126
	v_mov_b32_e32 v18, v126
	v_mov_b32_e32 v19, v126
	v_mov_b32_e32 v20, v126
	v_mov_b32_e32 v21, v126
	v_mov_b32_e32 v14, v126
	v_mov_b32_e32 v15, v126
	v_mov_b32_e32 v16, v126
	v_mov_b32_e32 v17, v126
	v_mov_b32_e32 v10, v126
	v_mov_b32_e32 v11, v126
	v_mov_b32_e32 v12, v126
	v_mov_b32_e32 v13, v126
	v_mov_b32_e32 v6, v126
	v_mov_b32_e32 v7, v126
	v_mov_b32_e32 v8, v126
	v_mov_b32_e32 v9, v126
	v_mov_b32_e32 v2, v126
	v_mov_b32_e32 v3, v126
	v_mov_b32_e32 v4, v126
	v_mov_b32_e32 v5, v126
	s_movk_i32 s17, 0xff80
	s_waitcnt vmcnt(0) lgkmcnt(0)
	s_barrier
	s_mov_b32 s47, 0
.LBB0_167:
	s_lshl_b32 s7, s45, 7
	s_add_u32 s14, s2, s7
	s_addc_u32 s15, s3, 0
	s_add_u32 s12, s0, s7
	s_addc_u32 s13, s1, 0
	v_readfirstlane_b32 s16, v147
	v_add_u32_e32 v0, v158, v159
	v_add_u32_e32 v177, v146, v160
	s_mov_b32 m0, s16
	s_cmp_eq_u32 s46, 0
	s_cbranch_scc1 .Lp2_first
	ds_read_b128 v[238:241], v177 offset:32768
	v_mfma_f32_16x16x32_bf16 v[122:125], v[242:245], v[178:181], v[122:125]
	global_load_lds_dwordx4 v130, s[14:15]
	s_add_u32 m0, m0, 0x2000
	v_mfma_f32_16x16x32_bf16 v[106:109], v[242:245], v[182:185], v[106:109]
	v_mfma_f32_16x16x32_bf16 v[90:93], v[242:245], v[186:189], v[90:93]
	v_mfma_f32_16x16x32_bf16 v[74:77], v[242:245], v[190:193], v[74:77]
	global_load_lds_dwordx4 v132, s[14:15]
	s_add_u32 m0, m0, 0x2000
	v_mfma_f32_16x16x32_bf16 v[58:61], v[242:245], v[222:225], v[58:61]
	v_mfma_f32_16x16x32_bf16 v[42:45], v[242:245], v[226:229], v[42:45]
	v_mfma_f32_16x16x32_bf16 v[26:29], v[242:245], v[230:233], v[26:29]
	global_load_lds_dwordx4 v134, s[14:15]
	s_add_u32 m0, m0, 0x2000
	v_mfma_f32_16x16x32_bf16 v[10:13], v[242:245], v[234:237], v[10:13]
	ds_read_b128 v[242:245], v177 offset:34816
	v_mfma_f32_16x16x32_bf16 v[118:121], v[246:249], v[178:181], v[118:121]
	v_mfma_f32_16x16x32_bf16 v[114:117], v[212:215], v[178:181], v[114:117]
	global_load_lds_dwordx4 v136, s[14:15]
	s_add_u32 m0, m0, 0x2000
	ds_read_b128 v[178:181], v162
	v_mfma_f32_16x16x32_bf16 v[102:105], v[246:249], v[182:185], v[102:105]
	v_mfma_f32_16x16x32_bf16 v[98:101], v[212:215], v[182:185], v[98:101]
	ds_read_b128 v[182:185], v163
	v_mfma_f32_16x16x32_bf16 v[86:89], v[246:249], v[186:189], v[86:89]
	global_load_lds_dwordx4 v130, s[12:13]
	s_add_u32 m0, m0, 0x2000
	v_mfma_f32_16x16x32_bf16 v[82:85], v[212:215], v[186:189], v[82:85]
	ds_read_b128 v[186:189], v164
	v_mfma_f32_16x16x32_bf16 v[70:73], v[246:249], v[190:193], v[70:73]
	v_mfma_f32_16x16x32_bf16 v[66:69], v[212:215], v[190:193], v[66:69]
	global_load_lds_dwordx4 v132, s[12:13]
	s_add_u32 m0, m0, 0x2000
	ds_read_b128 v[190:193], v165
	v_mfma_f32_16x16x32_bf16 v[54:57], v[246:249], v[222:225], v[54:57]
	v_mfma_f32_16x16x32_bf16 v[50:53], v[212:215], v[222:225], v[50:53]
	ds_read_b128 v[222:225], v166
	v_mfma_f32_16x16x32_bf16 v[38:41], v[246:249], v[226:229], v[38:41]
	global_load_lds_dwordx4 v134, s[12:13]
	s_add_u32 m0, m0, 0x2000
	v_mfma_f32_16x16x32_bf16 v[34:37], v[212:215], v[226:229], v[34:37]
	ds_read_b128 v[226:229], v167
	v_mfma_f32_16x16x32_bf16 v[22:25], v[246:249], v[230:233], v[22:25]
	v_mfma_f32_16x16x32_bf16 v[18:21], v[212:215], v[230:233], v[18:21]
	global_load_lds_dwordx4 v136, s[12:13]
	ds_read_b128 v[230:233], v168
	v_mfma_f32_16x16x32_bf16 v[6:9], v[246:249], v[234:237], v[6:9]
	v_mfma_f32_16x16x32_bf16 v[2:5], v[212:215], v[234:237], v[2:5]
	ds_read_b128 v[234:237], v0
	ds_read_b128 v[246:249], v177 offset:36864
	ds_read_b128 v[212:215], v177 offset:38912
	s_add_i32 s6, s6, 1
	s_cmp_lg_u32 s6, 32
	s_cbranch_scc0 .Lp2_epi0

.Lp2_partb0:
	s_waitcnt lgkmcnt(9)
	v_mfma_f32_16x16x32_bf16 v[126:129], v[238:241], v[178:181], v[126:129]
	s_waitcnt lgkmcnt(8)
	v_mfma_f32_16x16x32_bf16 v[110:113], v[238:241], v[182:185], v[110:113]
	s_waitcnt lgkmcnt(7)
	v_mfma_f32_16x16x32_bf16 v[94:97], v[238:241], v[186:189], v[94:97]
	s_waitcnt lgkmcnt(6)
	v_mfma_f32_16x16x32_bf16 v[78:81], v[238:241], v[190:193], v[78:81]
	s_waitcnt lgkmcnt(5)
	v_mfma_f32_16x16x32_bf16 v[62:65], v[238:241], v[222:225], v[62:65]
	s_waitcnt lgkmcnt(4)
	v_mfma_f32_16x16x32_bf16 v[46:49], v[238:241], v[226:229], v[46:49]
	s_waitcnt lgkmcnt(3)
	v_mfma_f32_16x16x32_bf16 v[30:33], v[238:241], v[230:233], v[30:33]
	s_waitcnt lgkmcnt(2)
	v_mfma_f32_16x16x32_bf16 v[14:17], v[238:241], v[234:237], v[14:17]
	ds_read_b128 v[238:241], v177 offset:33792
	v_mfma_f32_16x16x32_bf16 v[122:125], v[242:245], v[178:181], v[122:125]
	v_mfma_f32_16x16x32_bf16 v[106:109], v[242:245], v[182:185], v[106:109]
	v_mfma_f32_16x16x32_bf16 v[90:93], v[242:245], v[186:189], v[90:93]
	v_mfma_f32_16x16x32_bf16 v[74:77], v[242:245], v[190:193], v[74:77]
	v_mfma_f32_16x16x32_bf16 v[58:61], v[242:245], v[222:225], v[58:61]
	v_mfma_f32_16x16x32_bf16 v[42:45], v[242:245], v[226:229], v[42:45]
	v_mfma_f32_16x16x32_bf16 v[26:29], v[242:245], v[230:233], v[26:29]
	v_mfma_f32_16x16x32_bf16 v[10:13], v[242:245], v[234:237], v[10:13]
	ds_read_b128 v[242:245], v177 offset:35840
	s_waitcnt lgkmcnt(3)
	v_mfma_f32_16x16x32_bf16 v[118:121], v[246:249], v[178:181], v[118:121]
	s_waitcnt lgkmcnt(2)
	v_mfma_f32_16x16x32_bf16 v[114:117], v[212:215], v[178:181], v[114:117]
	ds_read_b128 v[178:181], v162 offset:1024
	v_mfma_f32_16x16x32_bf16 v[102:105], v[246:249], v[182:185], v[102:105]
	v_mfma_f32_16x16x32_bf16 v[98:101], v[212:215], v[182:185], v[98:101]
	ds_read_b128 v[182:185], v163 offset:1024
	v_mfma_f32_16x16x32_bf16 v[86:89], v[246:249], v[186:189], v[86:89]
	v_mfma_f32_16x16x32_bf16 v[82:85], v[212:215], v[186:189], v[82:85]
	ds_read_b128 v[186:189], v164 offset:1024
	v_mfma_f32_16x16x32_bf16 v[70:73], v[246:249], v[190:193], v[70:73]
	v_mfma_f32_16x16x32_bf16 v[66:69], v[212:215], v[190:193], v[66:69]
	ds_read_b128 v[190:193], v165 offset:1024
	v_mfma_f32_16x16x32_bf16 v[54:57], v[246:249], v[222:225], v[54:57]
	v_mfma_f32_16x16x32_bf16 v[50:53], v[212:215], v[222:225], v[50:53]
	ds_read_b128 v[222:225], v166 offset:1024
	v_mfma_f32_16x16x32_bf16 v[38:41], v[246:249], v[226:229], v[38:41]
	v_mfma_f32_16x16x32_bf16 v[34:37], v[212:215], v[226:229], v[34:37]
	ds_read_b128 v[226:229], v167 offset:1024
	v_mfma_f32_16x16x32_bf16 v[22:25], v[246:249], v[230:233], v[22:25]
	v_mfma_f32_16x16x32_bf16 v[18:21], v[212:215], v[230:233], v[18:21]
	ds_read_b128 v[230:233], v168 offset:1024
	v_mfma_f32_16x16x32_bf16 v[6:9], v[246:249], v[234:237], v[6:9]
	v_mfma_f32_16x16x32_bf16 v[2:5], v[212:215], v[234:237], v[2:5]
	ds_read_b128 v[234:237], v0 offset:1024
	ds_read_b128 v[246:249], v177 offset:37888
	ds_read_b128 v[212:215], v177 offset:39936
	s_waitcnt lgkmcnt(9)
	v_mfma_f32_16x16x32_bf16 v[126:129], v[238:241], v[178:181], v[126:129]
	s_waitcnt lgkmcnt(8)
	v_mfma_f32_16x16x32_bf16 v[110:113], v[238:241], v[182:185], v[110:113]
	s_waitcnt lgkmcnt(7)
	v_mfma_f32_16x16x32_bf16 v[94:97], v[238:241], v[186:189], v[94:97]
	s_waitcnt lgkmcnt(6)
	v_mfma_f32_16x16x32_bf16 v[78:81], v[238:241], v[190:193], v[78:81]
	s_waitcnt lgkmcnt(5)
	v_mfma_f32_16x16x32_bf16 v[62:65], v[238:241], v[222:225], v[62:65]
	s_waitcnt lgkmcnt(4)
	v_mfma_f32_16x16x32_bf16 v[46:49], v[238:241], v[226:229], v[46:49]
	s_waitcnt lgkmcnt(3)
	v_mfma_f32_16x16x32_bf16 v[30:33], v[238:241], v[230:233], v[30:33]
	s_waitcnt lgkmcnt(2)
	v_mfma_f32_16x16x32_bf16 v[14:17], v[238:241], v[234:237], v[14:17]
	s_add_i32 s45, s45, 1
	s_cmp_lg_u32 s45, 32
	s_cbranch_scc1 .Lp2_nowrap0
	s_add_i32 s22, s22, 1
	s_cmp_ge_i32 s22, s57
	s_cbranch_scc1 .Lp2_segdone0
	s_mul_i32 s0, s22, s62
	s_add_i32 s1, s0, s86
	s_mul_hi_i32 s0, s1, 0x2aaaaaab
	s_lshr_b32 s2, s0, 31
	s_ashr_i32 s0, s0, 3
	s_add_i32 s0, s0, s2
	s_mul_i32 s2, s0, 48
	s_sub_i32 s2, s1, s2
	s_ashr_i32 s3, s2, 31
	s_ashr_i32 s1, s0, 31
	s_lshl_b64 s[2:3], s[2:3], 20
	s_lshl_b64 s[0:1], s[0:1], 20
	v_readlane_b32 s12, v254, 3
	v_readlane_b32 s13, v254, 4
	s_add_u32 s2, s12, s2
	s_addc_u32 s3, s13, s3
	s_add_u32 s0, s11, s0
	s_addc_u32 s1, s21, s1

.Lp2_nowrap0:
	s_cmp_lg_u32 s47, 0
	s_cbranch_scc1 .Lp2_wepi0
	s_waitcnt vmcnt(0) lgkmcnt(0)
.Lp2_wjoin0:
	s_barrier
	s_add_i32 s46, s46, 1
.Lp2_body1:
	s_lshl_b32 s7, s45, 7
	s_add_u32 s14, s2, s7
	s_addc_u32 s15, s3, 0
	s_add_u32 s12, s0, s7
	s_addc_u32 s13, s1, 0
	v_readfirstlane_b32 s16, v138
	v_add_u32_e32 v0, v161, v157
	s_mov_b32 m0, s16
	ds_read_b128 v[238:241], v176
	v_mfma_f32_16x16x32_bf16 v[122:125], v[242:245], v[178:181], v[122:125]
	global_load_lds_dwordx4 v130, s[14:15]
	s_add_u32 m0, m0, 0x2000
	v_mfma_f32_16x16x32_bf16 v[106:109], v[242:245], v[182:185], v[106:109]
	v_mfma_f32_16x16x32_bf16 v[90:93], v[242:245], v[186:189], v[90:93]
	v_mfma_f32_16x16x32_bf16 v[74:77], v[242:245], v[190:193], v[74:77]
	global_load_lds_dwordx4 v132, s[14:15]
	s_add_u32 m0, m0, 0x2000
	v_mfma_f32_16x16x32_bf16 v[58:61], v[242:245], v[222:225], v[58:61]
	v_mfma_f32_16x16x32_bf16 v[42:45], v[242:245], v[226:229], v[42:45]
	v_mfma_f32_16x16x32_bf16 v[26:29], v[242:245], v[230:233], v[26:29]
	global_load_lds_dwordx4 v134, s[14:15]
	s_add_u32 m0, m0, 0x2000
	v_mfma_f32_16x16x32_bf16 v[10:13], v[242:245], v[234:237], v[10:13]
	ds_read_b128 v[242:245], v176 offset:2048
	v_mfma_f32_16x16x32_bf16 v[118:121], v[246:249], v[178:181], v[118:121]
	v_mfma_f32_16x16x32_bf16 v[114:117], v[212:215], v[178:181], v[114:117]
	global_load_lds_dwordx4 v136, s[14:15]
	s_add_u32 m0, m0, 0x2000
	ds_read_b128 v[178:181], v169
	v_mfma_f32_16x16x32_bf16 v[102:105], v[246:249], v[182:185], v[102:105]
	v_mfma_f32_16x16x32_bf16 v[98:101], v[212:215], v[182:185], v[98:101]
	ds_read_b128 v[182:185], v0
	v_mfma_f32_16x16x32_bf16 v[86:89], v[246:249], v[186:189], v[86:89]
	global_load_lds_dwordx4 v130, s[12:13]
	s_add_u32 m0, m0, 0x2000
	v_mfma_f32_16x16x32_bf16 v[82:85], v[212:215], v[186:189], v[82:85]
	ds_read_b128 v[186:189], v170
	v_mfma_f32_16x16x32_bf16 v[70:73], v[246:249], v[190:193], v[70:73]
	v_mfma_f32_16x16x32_bf16 v[66:69], v[212:215], v[190:193], v[66:69]
	global_load_lds_dwordx4 v132, s[12:13]
	s_add_u32 m0, m0, 0x2000
	ds_read_b128 v[190:193], v171
	v_mfma_f32_16x16x32_bf16 v[54:57], v[246:249], v[222:225], v[54:57]
	v_mfma_f32_16x16x32_bf16 v[50:53], v[212:215], v[222:225], v[50:53]
	ds_read_b128 v[222:225], v172
	v_mfma_f32_16x16x32_bf16 v[38:41], v[246:249], v[226:229], v[38:41]
	global_load_lds_dwordx4 v134, s[12:13]
	s_add_u32 m0, m0, 0x2000
	v_mfma_f32_16x16x32_bf16 v[34:37], v[212:215], v[226:229], v[34:37]
	ds_read_b128 v[226:229], v173
	v_mfma_f32_16x16x32_bf16 v[22:25], v[246:249], v[230:233], v[22:25]
	v_mfma_f32_16x16x32_bf16 v[18:21], v[212:215], v[230:233], v[18:21]
	global_load_lds_dwordx4 v136, s[12:13]
	ds_read_b128 v[230:233], v174
	v_mfma_f32_16x16x32_bf16 v[6:9], v[246:249], v[234:237], v[6:9]
	v_mfma_f32_16x16x32_bf16 v[2:5], v[212:215], v[234:237], v[2:5]
	ds_read_b128 v[234:237], v175
	ds_read_b128 v[246:249], v176 offset:4096
	ds_read_b128 v[212:215], v176 offset:6144
	s_add_i32 s6, s6, 1
	s_cmp_lg_u32 s6, 32
	s_cbranch_scc0 .Lp2_epi1

.Lp2_partb1:
	s_waitcnt lgkmcnt(9)
	v_mfma_f32_16x16x32_bf16 v[126:129], v[238:241], v[178:181], v[126:129]
	s_waitcnt lgkmcnt(8)
	v_mfma_f32_16x16x32_bf16 v[110:113], v[238:241], v[182:185], v[110:113]
	s_waitcnt lgkmcnt(7)
	v_mfma_f32_16x16x32_bf16 v[94:97], v[238:241], v[186:189], v[94:97]
	s_waitcnt lgkmcnt(6)
	v_mfma_f32_16x16x32_bf16 v[78:81], v[238:241], v[190:193], v[78:81]
	s_waitcnt lgkmcnt(5)
	v_mfma_f32_16x16x32_bf16 v[62:65], v[238:241], v[222:225], v[62:65]
	s_waitcnt lgkmcnt(4)
	v_mfma_f32_16x16x32_bf16 v[46:49], v[238:241], v[226:229], v[46:49]
	s_waitcnt lgkmcnt(3)
	v_mfma_f32_16x16x32_bf16 v[30:33], v[238:241], v[230:233], v[30:33]
	s_waitcnt lgkmcnt(2)
	v_mfma_f32_16x16x32_bf16 v[14:17], v[238:241], v[234:237], v[14:17]
	ds_read_b128 v[238:241], v176 offset:1024
	v_mfma_f32_16x16x32_bf16 v[122:125], v[242:245], v[178:181], v[122:125]
	v_mfma_f32_16x16x32_bf16 v[106:109], v[242:245], v[182:185], v[106:109]
	v_mfma_f32_16x16x32_bf16 v[90:93], v[242:245], v[186:189], v[90:93]
	v_mfma_f32_16x16x32_bf16 v[74:77], v[242:245], v[190:193], v[74:77]
	v_mfma_f32_16x16x32_bf16 v[58:61], v[242:245], v[222:225], v[58:61]
	v_mfma_f32_16x16x32_bf16 v[42:45], v[242:245], v[226:229], v[42:45]
	v_mfma_f32_16x16x32_bf16 v[26:29], v[242:245], v[230:233], v[26:29]
	v_mfma_f32_16x16x32_bf16 v[10:13], v[242:245], v[234:237], v[10:13]
	ds_read_b128 v[242:245], v176 offset:3072
	s_waitcnt lgkmcnt(3)
	v_mfma_f32_16x16x32_bf16 v[118:121], v[246:249], v[178:181], v[118:121]
	s_waitcnt lgkmcnt(2)
	v_mfma_f32_16x16x32_bf16 v[114:117], v[212:215], v[178:181], v[114:117]
	ds_read_b128 v[178:181], v169 offset:1024
	v_mfma_f32_16x16x32_bf16 v[102:105], v[246:249], v[182:185], v[102:105]
	v_mfma_f32_16x16x32_bf16 v[98:101], v[212:215], v[182:185], v[98:101]
	ds_read_b128 v[182:185], v0 offset:1024
	v_mfma_f32_16x16x32_bf16 v[86:89], v[246:249], v[186:189], v[86:89]
	v_mfma_f32_16x16x32_bf16 v[82:85], v[212:215], v[186:189], v[82:85]
	ds_read_b128 v[186:189], v170 offset:1024
	v_mfma_f32_16x16x32_bf16 v[70:73], v[246:249], v[190:193], v[70:73]
	v_mfma_f32_16x16x32_bf16 v[66:69], v[212:215], v[190:193], v[66:69]
	ds_read_b128 v[190:193], v171 offset:1024
	v_mfma_f32_16x16x32_bf16 v[54:57], v[246:249], v[222:225], v[54:57]
	v_mfma_f32_16x16x32_bf16 v[50:53], v[212:215], v[222:225], v[50:53]
	ds_read_b128 v[222:225], v172 offset:1024
	v_mfma_f32_16x16x32_bf16 v[38:41], v[246:249], v[226:229], v[38:41]
	v_mfma_f32_16x16x32_bf16 v[34:37], v[212:215], v[226:229], v[34:37]
	ds_read_b128 v[226:229], v173 offset:1024
	v_mfma_f32_16x16x32_bf16 v[22:25], v[246:249], v[230:233], v[22:25]
	v_mfma_f32_16x16x32_bf16 v[18:21], v[212:215], v[230:233], v[18:21]
	ds_read_b128 v[230:233], v174 offset:1024
	v_mfma_f32_16x16x32_bf16 v[6:9], v[246:249], v[234:237], v[6:9]
	v_mfma_f32_16x16x32_bf16 v[2:5], v[212:215], v[234:237], v[2:5]
	ds_read_b128 v[234:237], v175 offset:1024
	ds_read_b128 v[246:249], v176 offset:5120
	ds_read_b128 v[212:215], v176 offset:7168
	s_waitcnt lgkmcnt(9)
	v_mfma_f32_16x16x32_bf16 v[126:129], v[238:241], v[178:181], v[126:129]
	s_waitcnt lgkmcnt(8)
	v_mfma_f32_16x16x32_bf16 v[110:113], v[238:241], v[182:185], v[110:113]
	s_waitcnt lgkmcnt(7)
	v_mfma_f32_16x16x32_bf16 v[94:97], v[238:241], v[186:189], v[94:97]
	s_waitcnt lgkmcnt(6)
	v_mfma_f32_16x16x32_bf16 v[78:81], v[238:241], v[190:193], v[78:81]
	s_waitcnt lgkmcnt(5)
	v_mfma_f32_16x16x32_bf16 v[62:65], v[238:241], v[222:225], v[62:65]
	s_waitcnt lgkmcnt(4)
	v_mfma_f32_16x16x32_bf16 v[46:49], v[238:241], v[226:229], v[46:49]
	s_waitcnt lgkmcnt(3)
	v_mfma_f32_16x16x32_bf16 v[30:33], v[238:241], v[230:233], v[30:33]
	s_waitcnt lgkmcnt(2)
	v_mfma_f32_16x16x32_bf16 v[14:17], v[238:241], v[234:237], v[14:17]
	s_add_i32 s45, s45, 1
	s_cmp_lg_u32 s45, 32
	s_cbranch_scc1 .Lp2_nowrap1
	s_add_i32 s22, s22, 1
	s_cmp_ge_i32 s22, s57
	s_cbranch_scc1 .Lp2_segdone1
	s_mul_i32 s0, s22, s62
	s_add_i32 s1, s0, s86
	s_mul_hi_i32 s0, s1, 0x2aaaaaab
	s_lshr_b32 s2, s0, 31
	s_ashr_i32 s0, s0, 3
	s_add_i32 s0, s0, s2
	s_mul_i32 s2, s0, 48
	s_sub_i32 s2, s1, s2
	s_ashr_i32 s3, s2, 31
	s_ashr_i32 s1, s0, 31
	s_lshl_b64 s[2:3], s[2:3], 20
	s_lshl_b64 s[0:1], s[0:1], 20
	v_readlane_b32 s12, v254, 3
	v_readlane_b32 s13, v254, 4
	s_add_u32 s2, s12, s2
	s_addc_u32 s3, s13, s3
	s_add_u32 s0, s11, s0
	s_addc_u32 s1, s21, s1

.Lp2_wjoin1:
	s_barrier
	s_add_i32 s46, s46, 1
	s_branch .LBB0_167
.Lp2_first:
	ds_read_b128 v[238:241], v177 offset:32768
	global_load_lds_dwordx4 v130, s[14:15]
	s_add_u32 m0, m0, 0x2000
	s_nop 0
	global_load_lds_dwordx4 v132, s[14:15]
	s_add_u32 m0, m0, 0x2000
	s_nop 0
	global_load_lds_dwordx4 v134, s[14:15]
	s_add_u32 m0, m0, 0x2000
	s_nop 0
	global_load_lds_dwordx4 v136, s[14:15]
	s_add_u32 m0, m0, 0x2000
	s_nop 0
	global_load_lds_dwordx4 v130, s[12:13]
	s_add_u32 m0, m0, 0x2000
	s_nop 0
	global_load_lds_dwordx4 v132, s[12:13]
	s_add_u32 m0, m0, 0x2000
	s_nop 0
	global_load_lds_dwordx4 v134, s[12:13]
	s_add_u32 m0, m0, 0x2000
	s_nop 0
	global_load_lds_dwordx4 v136, s[12:13]
	s_add_u32 m0, m0, 0x2000
	s_nop 0
	ds_read_b128 v[242:245], v177 offset:34816
	ds_read_b128 v[178:181], v162
	ds_read_b128 v[182:185], v163
	ds_read_b128 v[186:189], v164
	ds_read_b128 v[190:193], v165
	ds_read_b128 v[222:225], v166
	ds_read_b128 v[226:229], v167
	ds_read_b128 v[230:233], v168
	ds_read_b128 v[234:237], v0
	ds_read_b128 v[246:249], v177 offset:36864
	ds_read_b128 v[212:215], v177 offset:38912
	s_branch .Lp2_partb0
.Lp2_epi0:
	s_nop 7
	s_nop 7
	s_mul_i32 s13, s44, s62
	s_add_i32 s13, s13, s86
	s_mul_hi_i32 s40, s13, 0x2aaaaaab
	s_lshr_b32 s41, s40, 31
	s_ashr_i32 s40, s40, 3
	s_add_i32 s40, s40, s41
	s_mul_i32 s41, s40, 48
	s_sub_i32 s41, s13, s41
	s_mul_i32 s41, s41, 0x780000
	s_lshl_b32 s7, s40, 9
	s_add_u32 s41, s41, s7
	s_add_u32 s14, s96, s41
	s_addc_u32 s15, s97, 0
	v_lshrrev_b32_e32 v0, 8, v196
	v_and_b32_e32 v177, 15, v196
	v_lshl_or_b32 v0, v0, 7, v177
	v_mul_u32_u24_e32 v0, 0x7800, v0
	v_bfe_u32 v177, v196, 6, 2
	v_lshl_add_u32 v0, v177, 7, v0
	v_bfe_u32 v177, v196, 4, 2
	v_lshl_add_u32 v0, v177, 3, v0
	v_and_b32_e32 v177, 1, v177
	v_mul_u32_u24_e32 v177, 24, v177
	v_add_u32_e32 v0, v0, v177
	s_cmp_lt_i32 s40, 28
	s_cbranch_scc1 .Lp2_epi0_plain
	v_mul_f32_e32 v126, 0xbfb8aa3b, v126
	v_mul_f32_e32 v127, 0xbfb8aa3b, v127
	v_mul_f32_e32 v128, 0xbfb8aa3b, v128
	v_mul_f32_e32 v129, 0xbfb8aa3b, v129
	v_exp_f32_e32 v126, v126
	v_exp_f32_e32 v127, v127
	v_exp_f32_e32 v128, v128
	v_exp_f32_e32 v129, v129
	v_add_f32_e32 v126, 1.0, v126
	v_add_f32_e32 v127, 1.0, v127
	v_add_f32_e32 v128, 1.0, v128
	v_add_f32_e32 v129, 1.0, v129
	v_rcp_f32_e32 v126, v126
	v_rcp_f32_e32 v127, v127
	v_rcp_f32_e32 v128, v128
	v_rcp_f32_e32 v129, v129
	v_mul_f32_e32 v122, 0xbfb8aa3b, v122
	v_mul_f32_e32 v123, 0xbfb8aa3b, v123
	v_mul_f32_e32 v124, 0xbfb8aa3b, v124
	v_mul_f32_e32 v125, 0xbfb8aa3b, v125
	v_exp_f32_e32 v122, v122
	v_exp_f32_e32 v123, v123
	v_exp_f32_e32 v124, v124
	v_exp_f32_e32 v125, v125
	v_add_f32_e32 v122, 1.0, v122
	v_add_f32_e32 v123, 1.0, v123
	v_add_f32_e32 v124, 1.0, v124
	v_add_f32_e32 v125, 1.0, v125
	v_rcp_f32_e32 v122, v122
	v_rcp_f32_e32 v123, v123
	v_rcp_f32_e32 v124, v124
	v_rcp_f32_e32 v125, v125
	v_mul_f32_e32 v118, 0xbfb8aa3b, v118
	v_mul_f32_e32 v119, 0xbfb8aa3b, v119
	v_mul_f32_e32 v120, 0xbfb8aa3b, v120
	v_mul_f32_e32 v121, 0xbfb8aa3b, v121
	v_exp_f32_e32 v118, v118
	v_exp_f32_e32 v119, v119
	v_exp_f32_e32 v120, v120
	v_exp_f32_e32 v121, v121
	v_add_f32_e32 v118, 1.0, v118
	v_add_f32_e32 v119, 1.0, v119
	v_add_f32_e32 v120, 1.0, v120
	v_add_f32_e32 v121, 1.0, v121
	v_rcp_f32_e32 v118, v118
	v_rcp_f32_e32 v119, v119
	v_rcp_f32_e32 v120, v120
	v_rcp_f32_e32 v121, v121
	v_mul_f32_e32 v114, 0xbfb8aa3b, v114
	v_mul_f32_e32 v115, 0xbfb8aa3b, v115
	v_mul_f32_e32 v116, 0xbfb8aa3b, v116
	v_mul_f32_e32 v117, 0xbfb8aa3b, v117
	v_exp_f32_e32 v114, v114
	v_exp_f32_e32 v115, v115
	v_exp_f32_e32 v116, v116
	v_exp_f32_e32 v117, v117
	v_add_f32_e32 v114, 1.0, v114
	v_add_f32_e32 v115, 1.0, v115
	v_add_f32_e32 v116, 1.0, v116
	v_add_f32_e32 v117, 1.0, v117
	v_rcp_f32_e32 v114, v114
	v_rcp_f32_e32 v115, v115
	v_rcp_f32_e32 v116, v116
	v_rcp_f32_e32 v117, v117
	v_cvt_pk_bf16_f32 v126, v126, v127
	v_cvt_pk_bf16_f32 v127, v128, v129
	v_cvt_pk_bf16_f32 v128, v122, v123
	v_cvt_pk_bf16_f32 v129, v124, v125
	v_cvt_pk_bf16_f32 v118, v118, v119
	v_cvt_pk_bf16_f32 v119, v120, v121
	v_cvt_pk_bf16_f32 v120, v114, v115
	v_cvt_pk_bf16_f32 v121, v116, v117
	s_nop 1
	v_permlane16_swap_b32_e32 v126, v128
	v_permlane16_swap_b32_e32 v127, v129
	v_permlane16_swap_b32_e32 v118, v120
	v_permlane16_swap_b32_e32 v119, v121
	global_store_dwordx4 v0, v[126:129], s[14:15]
	global_store_dwordx4 v0, v[118:121], s[14:15] offset:64
	v_mov_b32_e32 v122, 0
	v_mov_b32_e32 v123, 0
	v_mov_b32_e32 v124, 0
	v_mov_b32_e32 v125, 0
	v_mov_b32_e32 v114, 0
	v_mov_b32_e32 v115, 0
	v_mov_b32_e32 v116, 0
	v_mov_b32_e32 v117, 0
	v_mov_b32_e32 v126, 0
	v_mov_b32_e32 v127, 0
	v_mov_b32_e32 v128, 0
	v_mov_b32_e32 v129, 0
	v_mov_b32_e32 v118, 0
	v_mov_b32_e32 v119, 0
	v_mov_b32_e32 v120, 0
	v_mov_b32_e32 v121, 0
	s_add_u32 s14, s14, 0x78000
	s_addc_u32 s15, s15, 0
	v_mul_f32_e32 v110, 0xbfb8aa3b, v110
	v_mul_f32_e32 v111, 0xbfb8aa3b, v111
	v_mul_f32_e32 v112, 0xbfb8aa3b, v112
	v_mul_f32_e32 v113, 0xbfb8aa3b, v113
	v_exp_f32_e32 v110, v110
	v_exp_f32_e32 v111, v111
	v_exp_f32_e32 v112, v112
	v_exp_f32_e32 v113, v113
	v_add_f32_e32 v110, 1.0, v110
	v_add_f32_e32 v111, 1.0, v111
	v_add_f32_e32 v112, 1.0, v112
	v_add_f32_e32 v113, 1.0, v113
	v_rcp_f32_e32 v110, v110
	v_rcp_f32_e32 v111, v111
	v_rcp_f32_e32 v112, v112
	v_rcp_f32_e32 v113, v113
	v_mul_f32_e32 v106, 0xbfb8aa3b, v106
	v_mul_f32_e32 v107, 0xbfb8aa3b, v107
	v_mul_f32_e32 v108, 0xbfb8aa3b, v108
	v_mul_f32_e32 v109, 0xbfb8aa3b, v109
	v_exp_f32_e32 v106, v106
	v_exp_f32_e32 v107, v107
	v_exp_f32_e32 v108, v108
	v_exp_f32_e32 v109, v109
	v_add_f32_e32 v106, 1.0, v106
	v_add_f32_e32 v107, 1.0, v107
	v_add_f32_e32 v108, 1.0, v108
	v_add_f32_e32 v109, 1.0, v109
	v_rcp_f32_e32 v106, v106
	v_rcp_f32_e32 v107, v107
	v_rcp_f32_e32 v108, v108
	v_rcp_f32_e32 v109, v109
	v_mul_f32_e32 v102, 0xbfb8aa3b, v102
	v_mul_f32_e32 v103, 0xbfb8aa3b, v103
	v_mul_f32_e32 v104, 0xbfb8aa3b, v104
	v_mul_f32_e32 v105, 0xbfb8aa3b, v105
	v_exp_f32_e32 v102, v102
	v_exp_f32_e32 v103, v103
	v_exp_f32_e32 v104, v104
	v_exp_f32_e32 v105, v105
	v_add_f32_e32 v102, 1.0, v102
	v_add_f32_e32 v103, 1.0, v103
	v_add_f32_e32 v104, 1.0, v104
	v_add_f32_e32 v105, 1.0, v105
	v_rcp_f32_e32 v102, v102
	v_rcp_f32_e32 v103, v103
	v_rcp_f32_e32 v104, v104
	v_rcp_f32_e32 v105, v105
	v_mul_f32_e32 v98, 0xbfb8aa3b, v98
	v_mul_f32_e32 v99, 0xbfb8aa3b, v99
	v_mul_f32_e32 v100, 0xbfb8aa3b, v100
	v_mul_f32_e32 v101, 0xbfb8aa3b, v101
	v_exp_f32_e32 v98, v98
	v_exp_f32_e32 v99, v99
	v_exp_f32_e32 v100, v100
	v_exp_f32_e32 v101, v101
	v_add_f32_e32 v98, 1.0, v98
	v_add_f32_e32 v99, 1.0, v99
	v_add_f32_e32 v100, 1.0, v100
	v_add_f32_e32 v101, 1.0, v101
	v_rcp_f32_e32 v98, v98
	v_rcp_f32_e32 v99, v99
	v_rcp_f32_e32 v100, v100
	v_rcp_f32_e32 v101, v101
	v_cvt_pk_bf16_f32 v110, v110, v111
	v_cvt_pk_bf16_f32 v111, v112, v113
	v_cvt_pk_bf16_f32 v112, v106, v107
	v_cvt_pk_bf16_f32 v113, v108, v109
	v_cvt_pk_bf16_f32 v102, v102, v103
	v_cvt_pk_bf16_f32 v103, v104, v105
	v_cvt_pk_bf16_f32 v104, v98, v99
	v_cvt_pk_bf16_f32 v105, v100, v101
	s_nop 1
	v_permlane16_swap_b32_e32 v110, v112
	v_permlane16_swap_b32_e32 v111, v113
	v_permlane16_swap_b32_e32 v102, v104
	v_permlane16_swap_b32_e32 v103, v105
	global_store_dwordx4 v0, v[110:113], s[14:15]
	global_store_dwordx4 v0, v[102:105], s[14:15] offset:64
	v_mov_b32_e32 v106, 0
	v_mov_b32_e32 v107, 0
	v_mov_b32_e32 v108, 0
	v_mov_b32_e32 v109, 0
	v_mov_b32_e32 v98, 0
	v_mov_b32_e32 v99, 0
	v_mov_b32_e32 v100, 0
	v_mov_b32_e32 v101, 0
	v_mov_b32_e32 v110, 0
	v_mov_b32_e32 v111, 0
	v_mov_b32_e32 v112, 0
	v_mov_b32_e32 v113, 0
	v_mov_b32_e32 v102, 0
	v_mov_b32_e32 v103, 0
	v_mov_b32_e32 v104, 0
	v_mov_b32_e32 v105, 0
	s_add_u32 s14, s14, 0x78000
	s_addc_u32 s15, s15, 0
	v_mul_f32_e32 v94, 0xbfb8aa3b, v94
	v_mul_f32_e32 v95, 0xbfb8aa3b, v95
	v_mul_f32_e32 v96, 0xbfb8aa3b, v96
	v_mul_f32_e32 v97, 0xbfb8aa3b, v97
	v_exp_f32_e32 v94, v94
	v_exp_f32_e32 v95, v95
	v_exp_f32_e32 v96, v96
	v_exp_f32_e32 v97, v97
	v_add_f32_e32 v94, 1.0, v94
	v_add_f32_e32 v95, 1.0, v95
	v_add_f32_e32 v96, 1.0, v96
	v_add_f32_e32 v97, 1.0, v97
	v_rcp_f32_e32 v94, v94
	v_rcp_f32_e32 v95, v95
	v_rcp_f32_e32 v96, v96
	v_rcp_f32_e32 v97, v97
	v_mul_f32_e32 v90, 0xbfb8aa3b, v90
	v_mul_f32_e32 v91, 0xbfb8aa3b, v91
	v_mul_f32_e32 v92, 0xbfb8aa3b, v92
	v_mul_f32_e32 v93, 0xbfb8aa3b, v93
	v_exp_f32_e32 v90, v90
	v_exp_f32_e32 v91, v91
	v_exp_f32_e32 v92, v92
	v_exp_f32_e32 v93, v93
	v_add_f32_e32 v90, 1.0, v90
	v_add_f32_e32 v91, 1.0, v91
	v_add_f32_e32 v92, 1.0, v92
	v_add_f32_e32 v93, 1.0, v93
	v_rcp_f32_e32 v90, v90
	v_rcp_f32_e32 v91, v91
	v_rcp_f32_e32 v92, v92
	v_rcp_f32_e32 v93, v93
	v_mul_f32_e32 v86, 0xbfb8aa3b, v86
	v_mul_f32_e32 v87, 0xbfb8aa3b, v87
	v_mul_f32_e32 v88, 0xbfb8aa3b, v88
	v_mul_f32_e32 v89, 0xbfb8aa3b, v89
	v_exp_f32_e32 v86, v86
	v_exp_f32_e32 v87, v87
	v_exp_f32_e32 v88, v88
	v_exp_f32_e32 v89, v89
	v_add_f32_e32 v86, 1.0, v86
	v_add_f32_e32 v87, 1.0, v87
	v_add_f32_e32 v88, 1.0, v88
	v_add_f32_e32 v89, 1.0, v89
	v_rcp_f32_e32 v86, v86
	v_rcp_f32_e32 v87, v87
	v_rcp_f32_e32 v88, v88
	v_rcp_f32_e32 v89, v89
	v_mul_f32_e32 v82, 0xbfb8aa3b, v82
	v_mul_f32_e32 v83, 0xbfb8aa3b, v83
	v_mul_f32_e32 v84, 0xbfb8aa3b, v84
	v_mul_f32_e32 v85, 0xbfb8aa3b, v85
	v_exp_f32_e32 v82, v82
	v_exp_f32_e32 v83, v83
	v_exp_f32_e32 v84, v84
	v_exp_f32_e32 v85, v85
	v_add_f32_e32 v82, 1.0, v82
	v_add_f32_e32 v83, 1.0, v83
	v_add_f32_e32 v84, 1.0, v84
	v_add_f32_e32 v85, 1.0, v85
	v_rcp_f32_e32 v82, v82
	v_rcp_f32_e32 v83, v83
	v_rcp_f32_e32 v84, v84
	v_rcp_f32_e32 v85, v85
	v_cvt_pk_bf16_f32 v94, v94, v95
	v_cvt_pk_bf16_f32 v95, v96, v97
	v_cvt_pk_bf16_f32 v96, v90, v91
	v_cvt_pk_bf16_f32 v97, v92, v93
	v_cvt_pk_bf16_f32 v86, v86, v87
	v_cvt_pk_bf16_f32 v87, v88, v89
	v_cvt_pk_bf16_f32 v88, v82, v83
	v_cvt_pk_bf16_f32 v89, v84, v85
	s_nop 1
	v_permlane16_swap_b32_e32 v94, v96
	v_permlane16_swap_b32_e32 v95, v97
	v_permlane16_swap_b32_e32 v86, v88
	v_permlane16_swap_b32_e32 v87, v89
	global_store_dwordx4 v0, v[94:97], s[14:15]
	global_store_dwordx4 v0, v[86:89], s[14:15] offset:64
	v_mov_b32_e32 v90, 0
	v_mov_b32_e32 v91, 0
	v_mov_b32_e32 v92, 0
	v_mov_b32_e32 v93, 0
	v_mov_b32_e32 v82, 0
	v_mov_b32_e32 v83, 0
	v_mov_b32_e32 v84, 0
	v_mov_b32_e32 v85, 0
	v_mov_b32_e32 v94, 0
	v_mov_b32_e32 v95, 0
	v_mov_b32_e32 v96, 0
	v_mov_b32_e32 v97, 0
	v_mov_b32_e32 v86, 0
	v_mov_b32_e32 v87, 0
	v_mov_b32_e32 v88, 0
	v_mov_b32_e32 v89, 0
	s_add_u32 s14, s14, 0x78000
	s_addc_u32 s15, s15, 0
	v_mul_f32_e32 v78, 0xbfb8aa3b, v78
	v_mul_f32_e32 v79, 0xbfb8aa3b, v79
	v_mul_f32_e32 v80, 0xbfb8aa3b, v80
	v_mul_f32_e32 v81, 0xbfb8aa3b, v81
	v_exp_f32_e32 v78, v78
	v_exp_f32_e32 v79, v79
	v_exp_f32_e32 v80, v80
	v_exp_f32_e32 v81, v81
	v_add_f32_e32 v78, 1.0, v78
	v_add_f32_e32 v79, 1.0, v79
	v_add_f32_e32 v80, 1.0, v80
	v_add_f32_e32 v81, 1.0, v81
	v_rcp_f32_e32 v78, v78
	v_rcp_f32_e32 v79, v79
	v_rcp_f32_e32 v80, v80
	v_rcp_f32_e32 v81, v81
	v_mul_f32_e32 v74, 0xbfb8aa3b, v74
	v_mul_f32_e32 v75, 0xbfb8aa3b, v75
	v_mul_f32_e32 v76, 0xbfb8aa3b, v76
	v_mul_f32_e32 v77, 0xbfb8aa3b, v77
	v_exp_f32_e32 v74, v74
	v_exp_f32_e32 v75, v75
	v_exp_f32_e32 v76, v76
	v_exp_f32_e32 v77, v77
	v_add_f32_e32 v74, 1.0, v74
	v_add_f32_e32 v75, 1.0, v75
	v_add_f32_e32 v76, 1.0, v76
	v_add_f32_e32 v77, 1.0, v77
	v_rcp_f32_e32 v74, v74
	v_rcp_f32_e32 v75, v75
	v_rcp_f32_e32 v76, v76
	v_rcp_f32_e32 v77, v77
	v_mul_f32_e32 v70, 0xbfb8aa3b, v70
	v_mul_f32_e32 v71, 0xbfb8aa3b, v71
	v_mul_f32_e32 v72, 0xbfb8aa3b, v72
	v_mul_f32_e32 v73, 0xbfb8aa3b, v73
	v_exp_f32_e32 v70, v70
	v_exp_f32_e32 v71, v71
	v_exp_f32_e32 v72, v72
	v_exp_f32_e32 v73, v73
	v_add_f32_e32 v70, 1.0, v70
	v_add_f32_e32 v71, 1.0, v71
	v_add_f32_e32 v72, 1.0, v72
	v_add_f32_e32 v73, 1.0, v73
	v_rcp_f32_e32 v70, v70
	v_rcp_f32_e32 v71, v71
	v_rcp_f32_e32 v72, v72
	v_rcp_f32_e32 v73, v73
	v_mul_f32_e32 v66, 0xbfb8aa3b, v66
	v_mul_f32_e32 v67, 0xbfb8aa3b, v67
	v_mul_f32_e32 v68, 0xbfb8aa3b, v68
	v_mul_f32_e32 v69, 0xbfb8aa3b, v69
	v_exp_f32_e32 v66, v66
	v_exp_f32_e32 v67, v67
	v_exp_f32_e32 v68, v68
	v_exp_f32_e32 v69, v69
	v_add_f32_e32 v66, 1.0, v66
	v_add_f32_e32 v67, 1.0, v67
	v_add_f32_e32 v68, 1.0, v68
	v_add_f32_e32 v69, 1.0, v69
	v_rcp_f32_e32 v66, v66
	v_rcp_f32_e32 v67, v67
	v_rcp_f32_e32 v68, v68
	v_rcp_f32_e32 v69, v69
	v_cvt_pk_bf16_f32 v78, v78, v79
	v_cvt_pk_bf16_f32 v79, v80, v81
	v_cvt_pk_bf16_f32 v80, v74, v75
	v_cvt_pk_bf16_f32 v81, v76, v77
	v_cvt_pk_bf16_f32 v70, v70, v71
	v_cvt_pk_bf16_f32 v71, v72, v73
	v_cvt_pk_bf16_f32 v72, v66, v67
	v_cvt_pk_bf16_f32 v73, v68, v69
	s_nop 1
	v_permlane16_swap_b32_e32 v78, v80
	v_permlane16_swap_b32_e32 v79, v81
	v_permlane16_swap_b32_e32 v70, v72
	v_permlane16_swap_b32_e32 v71, v73
	global_store_dwordx4 v0, v[78:81], s[14:15]
	global_store_dwordx4 v0, v[70:73], s[14:15] offset:64
	v_mov_b32_e32 v74, 0
	v_mov_b32_e32 v75, 0
	v_mov_b32_e32 v76, 0
	v_mov_b32_e32 v77, 0
	v_mov_b32_e32 v66, 0
	v_mov_b32_e32 v67, 0
	v_mov_b32_e32 v68, 0
	v_mov_b32_e32 v69, 0
	v_mov_b32_e32 v78, 0
	v_mov_b32_e32 v79, 0
	v_mov_b32_e32 v80, 0
	v_mov_b32_e32 v81, 0
	v_mov_b32_e32 v70, 0
	v_mov_b32_e32 v71, 0
	v_mov_b32_e32 v72, 0
	v_mov_b32_e32 v73, 0
	s_add_u32 s14, s14, 0x78000
	s_addc_u32 s15, s15, 0
	v_mul_f32_e32 v62, 0xbfb8aa3b, v62
	v_mul_f32_e32 v63, 0xbfb8aa3b, v63
	v_mul_f32_e32 v64, 0xbfb8aa3b, v64
	v_mul_f32_e32 v65, 0xbfb8aa3b, v65
	v_exp_f32_e32 v62, v62
	v_exp_f32_e32 v63, v63
	v_exp_f32_e32 v64, v64
	v_exp_f32_e32 v65, v65
	v_add_f32_e32 v62, 1.0, v62
	v_add_f32_e32 v63, 1.0, v63
	v_add_f32_e32 v64, 1.0, v64
	v_add_f32_e32 v65, 1.0, v65
	v_rcp_f32_e32 v62, v62
	v_rcp_f32_e32 v63, v63
	v_rcp_f32_e32 v64, v64
	v_rcp_f32_e32 v65, v65
	v_mul_f32_e32 v58, 0xbfb8aa3b, v58
	v_mul_f32_e32 v59, 0xbfb8aa3b, v59
	v_mul_f32_e32 v60, 0xbfb8aa3b, v60
	v_mul_f32_e32 v61, 0xbfb8aa3b, v61
	v_exp_f32_e32 v58, v58
	v_exp_f32_e32 v59, v59
	v_exp_f32_e32 v60, v60
	v_exp_f32_e32 v61, v61
	v_add_f32_e32 v58, 1.0, v58
	v_add_f32_e32 v59, 1.0, v59
	v_add_f32_e32 v60, 1.0, v60
	v_add_f32_e32 v61, 1.0, v61
	v_rcp_f32_e32 v58, v58
	v_rcp_f32_e32 v59, v59
	v_rcp_f32_e32 v60, v60
	v_rcp_f32_e32 v61, v61
	v_mul_f32_e32 v54, 0xbfb8aa3b, v54
	v_mul_f32_e32 v55, 0xbfb8aa3b, v55
	v_mul_f32_e32 v56, 0xbfb8aa3b, v56
	v_mul_f32_e32 v57, 0xbfb8aa3b, v57
	v_exp_f32_e32 v54, v54
	v_exp_f32_e32 v55, v55
	v_exp_f32_e32 v56, v56
	v_exp_f32_e32 v57, v57
	v_add_f32_e32 v54, 1.0, v54
	v_add_f32_e32 v55, 1.0, v55
	v_add_f32_e32 v56, 1.0, v56
	v_add_f32_e32 v57, 1.0, v57
	v_rcp_f32_e32 v54, v54
	v_rcp_f32_e32 v55, v55
	v_rcp_f32_e32 v56, v56
	v_rcp_f32_e32 v57, v57
	v_mul_f32_e32 v50, 0xbfb8aa3b, v50
	v_mul_f32_e32 v51, 0xbfb8aa3b, v51
	v_mul_f32_e32 v52, 0xbfb8aa3b, v52
	v_mul_f32_e32 v53, 0xbfb8aa3b, v53
	v_exp_f32_e32 v50, v50
	v_exp_f32_e32 v51, v51
	v_exp_f32_e32 v52, v52
	v_exp_f32_e32 v53, v53
	v_add_f32_e32 v50, 1.0, v50
	v_add_f32_e32 v51, 1.0, v51
	v_add_f32_e32 v52, 1.0, v52
	v_add_f32_e32 v53, 1.0, v53
	v_rcp_f32_e32 v50, v50
	v_rcp_f32_e32 v51, v51
	v_rcp_f32_e32 v52, v52
	v_rcp_f32_e32 v53, v53
	v_cvt_pk_bf16_f32 v62, v62, v63
	v_cvt_pk_bf16_f32 v63, v64, v65
	v_cvt_pk_bf16_f32 v64, v58, v59
	v_cvt_pk_bf16_f32 v65, v60, v61
	v_cvt_pk_bf16_f32 v54, v54, v55
	v_cvt_pk_bf16_f32 v55, v56, v57
	v_cvt_pk_bf16_f32 v56, v50, v51
	v_cvt_pk_bf16_f32 v57, v52, v53
	s_nop 1
	v_permlane16_swap_b32_e32 v62, v64
	v_permlane16_swap_b32_e32 v63, v65
	v_permlane16_swap_b32_e32 v54, v56
	v_permlane16_swap_b32_e32 v55, v57
	global_store_dwordx4 v0, v[62:65], s[14:15]
	global_store_dwordx4 v0, v[54:57], s[14:15] offset:64
	v_mov_b32_e32 v58, 0
	v_mov_b32_e32 v59, 0
	v_mov_b32_e32 v60, 0
	v_mov_b32_e32 v61, 0
	v_mov_b32_e32 v50, 0
	v_mov_b32_e32 v51, 0
	v_mov_b32_e32 v52, 0
	v_mov_b32_e32 v53, 0
	v_mov_b32_e32 v62, 0
	v_mov_b32_e32 v63, 0
	v_mov_b32_e32 v64, 0
	v_mov_b32_e32 v65, 0
	v_mov_b32_e32 v54, 0
	v_mov_b32_e32 v55, 0
	v_mov_b32_e32 v56, 0
	v_mov_b32_e32 v57, 0
	s_add_u32 s14, s14, 0x78000
	s_addc_u32 s15, s15, 0
	v_mul_f32_e32 v46, 0xbfb8aa3b, v46
	v_mul_f32_e32 v47, 0xbfb8aa3b, v47
	v_mul_f32_e32 v48, 0xbfb8aa3b, v48
	v_mul_f32_e32 v49, 0xbfb8aa3b, v49
	v_exp_f32_e32 v46, v46
	v_exp_f32_e32 v47, v47
	v_exp_f32_e32 v48, v48
	v_exp_f32_e32 v49, v49
	v_add_f32_e32 v46, 1.0, v46
	v_add_f32_e32 v47, 1.0, v47
	v_add_f32_e32 v48, 1.0, v48
	v_add_f32_e32 v49, 1.0, v49
	v_rcp_f32_e32 v46, v46
	v_rcp_f32_e32 v47, v47
	v_rcp_f32_e32 v48, v48
	v_rcp_f32_e32 v49, v49
	v_mul_f32_e32 v42, 0xbfb8aa3b, v42
	v_mul_f32_e32 v43, 0xbfb8aa3b, v43
	v_mul_f32_e32 v44, 0xbfb8aa3b, v44
	v_mul_f32_e32 v45, 0xbfb8aa3b, v45
	v_exp_f32_e32 v42, v42
	v_exp_f32_e32 v43, v43
	v_exp_f32_e32 v44, v44
	v_exp_f32_e32 v45, v45
	v_add_f32_e32 v42, 1.0, v42
	v_add_f32_e32 v43, 1.0, v43
	v_add_f32_e32 v44, 1.0, v44
	v_add_f32_e32 v45, 1.0, v45
	v_rcp_f32_e32 v42, v42
	v_rcp_f32_e32 v43, v43
	v_rcp_f32_e32 v44, v44
	v_rcp_f32_e32 v45, v45
	v_mul_f32_e32 v38, 0xbfb8aa3b, v38
	v_mul_f32_e32 v39, 0xbfb8aa3b, v39
	v_mul_f32_e32 v40, 0xbfb8aa3b, v40
	v_mul_f32_e32 v41, 0xbfb8aa3b, v41
	v_exp_f32_e32 v38, v38
	v_exp_f32_e32 v39, v39
	v_exp_f32_e32 v40, v40
	v_exp_f32_e32 v41, v41
	v_add_f32_e32 v38, 1.0, v38
	v_add_f32_e32 v39, 1.0, v39
	v_add_f32_e32 v40, 1.0, v40
	v_add_f32_e32 v41, 1.0, v41
	v_rcp_f32_e32 v38, v38
	v_rcp_f32_e32 v39, v39
	v_rcp_f32_e32 v40, v40
	v_rcp_f32_e32 v41, v41
	v_mul_f32_e32 v34, 0xbfb8aa3b, v34
	v_mul_f32_e32 v35, 0xbfb8aa3b, v35
	v_mul_f32_e32 v36, 0xbfb8aa3b, v36
	v_mul_f32_e32 v37, 0xbfb8aa3b, v37
	v_exp_f32_e32 v34, v34
	v_exp_f32_e32 v35, v35
	v_exp_f32_e32 v36, v36
	v_exp_f32_e32 v37, v37
	v_add_f32_e32 v34, 1.0, v34
	v_add_f32_e32 v35, 1.0, v35
	v_add_f32_e32 v36, 1.0, v36
	v_add_f32_e32 v37, 1.0, v37
	v_rcp_f32_e32 v34, v34
	v_rcp_f32_e32 v35, v35
	v_rcp_f32_e32 v36, v36
	v_rcp_f32_e32 v37, v37
	v_cvt_pk_bf16_f32 v46, v46, v47
	v_cvt_pk_bf16_f32 v47, v48, v49
	v_cvt_pk_bf16_f32 v48, v42, v43
	v_cvt_pk_bf16_f32 v49, v44, v45
	v_cvt_pk_bf16_f32 v38, v38, v39
	v_cvt_pk_bf16_f32 v39, v40, v41
	v_cvt_pk_bf16_f32 v40, v34, v35
	v_cvt_pk_bf16_f32 v41, v36, v37
	s_nop 1
	v_permlane16_swap_b32_e32 v46, v48
	v_permlane16_swap_b32_e32 v47, v49
	v_permlane16_swap_b32_e32 v38, v40
	v_permlane16_swap_b32_e32 v39, v41
	global_store_dwordx4 v0, v[46:49], s[14:15]
	global_store_dwordx4 v0, v[38:41], s[14:15] offset:64
	v_mov_b32_e32 v42, 0
	v_mov_b32_e32 v43, 0
	v_mov_b32_e32 v44, 0
	v_mov_b32_e32 v45, 0
	v_mov_b32_e32 v34, 0
	v_mov_b32_e32 v35, 0
	v_mov_b32_e32 v36, 0
	v_mov_b32_e32 v37, 0
	v_mov_b32_e32 v46, 0
	v_mov_b32_e32 v47, 0
	v_mov_b32_e32 v48, 0
	v_mov_b32_e32 v49, 0
	v_mov_b32_e32 v38, 0
	v_mov_b32_e32 v39, 0
	v_mov_b32_e32 v40, 0
	v_mov_b32_e32 v41, 0
	s_add_u32 s14, s14, 0x78000
	s_addc_u32 s15, s15, 0
	v_mul_f32_e32 v30, 0xbfb8aa3b, v30
	v_mul_f32_e32 v31, 0xbfb8aa3b, v31
	v_mul_f32_e32 v32, 0xbfb8aa3b, v32
	v_mul_f32_e32 v33, 0xbfb8aa3b, v33
	v_exp_f32_e32 v30, v30
	v_exp_f32_e32 v31, v31
	v_exp_f32_e32 v32, v32
	v_exp_f32_e32 v33, v33
	v_add_f32_e32 v30, 1.0, v30
	v_add_f32_e32 v31, 1.0, v31
	v_add_f32_e32 v32, 1.0, v32
	v_add_f32_e32 v33, 1.0, v33
	v_rcp_f32_e32 v30, v30
	v_rcp_f32_e32 v31, v31
	v_rcp_f32_e32 v32, v32
	v_rcp_f32_e32 v33, v33
	v_mul_f32_e32 v26, 0xbfb8aa3b, v26
	v_mul_f32_e32 v27, 0xbfb8aa3b, v27
	v_mul_f32_e32 v28, 0xbfb8aa3b, v28
	v_mul_f32_e32 v29, 0xbfb8aa3b, v29
	v_exp_f32_e32 v26, v26
	v_exp_f32_e32 v27, v27
	v_exp_f32_e32 v28, v28
	v_exp_f32_e32 v29, v29
	v_add_f32_e32 v26, 1.0, v26
	v_add_f32_e32 v27, 1.0, v27
	v_add_f32_e32 v28, 1.0, v28
	v_add_f32_e32 v29, 1.0, v29
	v_rcp_f32_e32 v26, v26
	v_rcp_f32_e32 v27, v27
	v_rcp_f32_e32 v28, v28
	v_rcp_f32_e32 v29, v29
	v_mul_f32_e32 v22, 0xbfb8aa3b, v22
	v_mul_f32_e32 v23, 0xbfb8aa3b, v23
	v_mul_f32_e32 v24, 0xbfb8aa3b, v24
	v_mul_f32_e32 v25, 0xbfb8aa3b, v25
	v_exp_f32_e32 v22, v22
	v_exp_f32_e32 v23, v23
	v_exp_f32_e32 v24, v24
	v_exp_f32_e32 v25, v25
	v_add_f32_e32 v22, 1.0, v22
	v_add_f32_e32 v23, 1.0, v23
	v_add_f32_e32 v24, 1.0, v24
	v_add_f32_e32 v25, 1.0, v25
	v_rcp_f32_e32 v22, v22
	v_rcp_f32_e32 v23, v23
	v_rcp_f32_e32 v24, v24
	v_rcp_f32_e32 v25, v25
	v_mul_f32_e32 v18, 0xbfb8aa3b, v18
	v_mul_f32_e32 v19, 0xbfb8aa3b, v19
	v_mul_f32_e32 v20, 0xbfb8aa3b, v20
	v_mul_f32_e32 v21, 0xbfb8aa3b, v21
	v_exp_f32_e32 v18, v18
	v_exp_f32_e32 v19, v19
	v_exp_f32_e32 v20, v20
	v_exp_f32_e32 v21, v21
	v_add_f32_e32 v18, 1.0, v18
	v_add_f32_e32 v19, 1.0, v19
	v_add_f32_e32 v20, 1.0, v20
	v_add_f32_e32 v21, 1.0, v21
	v_rcp_f32_e32 v18, v18
	v_rcp_f32_e32 v19, v19
	v_rcp_f32_e32 v20, v20
	v_rcp_f32_e32 v21, v21
	v_cvt_pk_bf16_f32 v30, v30, v31
	v_cvt_pk_bf16_f32 v31, v32, v33
	v_cvt_pk_bf16_f32 v32, v26, v27
	v_cvt_pk_bf16_f32 v33, v28, v29
	v_cvt_pk_bf16_f32 v22, v22, v23
	v_cvt_pk_bf16_f32 v23, v24, v25
	v_cvt_pk_bf16_f32 v24, v18, v19
	v_cvt_pk_bf16_f32 v25, v20, v21
	s_nop 1
	v_permlane16_swap_b32_e32 v30, v32
	v_permlane16_swap_b32_e32 v31, v33
	v_permlane16_swap_b32_e32 v22, v24
	v_permlane16_swap_b32_e32 v23, v25
	global_store_dwordx4 v0, v[30:33], s[14:15]
	global_store_dwordx4 v0, v[22:25], s[14:15] offset:64
	v_mov_b32_e32 v26, 0
	v_mov_b32_e32 v27, 0
	v_mov_b32_e32 v28, 0
	v_mov_b32_e32 v29, 0
	v_mov_b32_e32 v18, 0
	v_mov_b32_e32 v19, 0
	v_mov_b32_e32 v20, 0
	v_mov_b32_e32 v21, 0
	v_mov_b32_e32 v30, 0
	v_mov_b32_e32 v31, 0
	v_mov_b32_e32 v32, 0
	v_mov_b32_e32 v33, 0
	v_mov_b32_e32 v22, 0
	v_mov_b32_e32 v23, 0
	v_mov_b32_e32 v24, 0
	v_mov_b32_e32 v25, 0
	s_add_u32 s14, s14, 0x78000
	s_addc_u32 s15, s15, 0
	v_mul_f32_e32 v14, 0xbfb8aa3b, v14
	v_mul_f32_e32 v15, 0xbfb8aa3b, v15
	v_mul_f32_e32 v16, 0xbfb8aa3b, v16
	v_mul_f32_e32 v17, 0xbfb8aa3b, v17
	v_exp_f32_e32 v14, v14
	v_exp_f32_e32 v15, v15
	v_exp_f32_e32 v16, v16
	v_exp_f32_e32 v17, v17
	v_add_f32_e32 v14, 1.0, v14
	v_add_f32_e32 v15, 1.0, v15
	v_add_f32_e32 v16, 1.0, v16
	v_add_f32_e32 v17, 1.0, v17
	v_rcp_f32_e32 v14, v14
	v_rcp_f32_e32 v15, v15
	v_rcp_f32_e32 v16, v16
	v_rcp_f32_e32 v17, v17
	v_mul_f32_e32 v10, 0xbfb8aa3b, v10
	v_mul_f32_e32 v11, 0xbfb8aa3b, v11
	v_mul_f32_e32 v12, 0xbfb8aa3b, v12
	v_mul_f32_e32 v13, 0xbfb8aa3b, v13
	v_exp_f32_e32 v10, v10
	v_exp_f32_e32 v11, v11
	v_exp_f32_e32 v12, v12
	v_exp_f32_e32 v13, v13
	v_add_f32_e32 v10, 1.0, v10
	v_add_f32_e32 v11, 1.0, v11
	v_add_f32_e32 v12, 1.0, v12
	v_add_f32_e32 v13, 1.0, v13
	v_rcp_f32_e32 v10, v10
	v_rcp_f32_e32 v11, v11
	v_rcp_f32_e32 v12, v12
	v_rcp_f32_e32 v13, v13
	v_mul_f32_e32 v6, 0xbfb8aa3b, v6
	v_mul_f32_e32 v7, 0xbfb8aa3b, v7
	v_mul_f32_e32 v8, 0xbfb8aa3b, v8
	v_mul_f32_e32 v9, 0xbfb8aa3b, v9
	v_exp_f32_e32 v6, v6
	v_exp_f32_e32 v7, v7
	v_exp_f32_e32 v8, v8
	v_exp_f32_e32 v9, v9
	v_add_f32_e32 v6, 1.0, v6
	v_add_f32_e32 v7, 1.0, v7
	v_add_f32_e32 v8, 1.0, v8
	v_add_f32_e32 v9, 1.0, v9
	v_rcp_f32_e32 v6, v6
	v_rcp_f32_e32 v7, v7
	v_rcp_f32_e32 v8, v8
	v_rcp_f32_e32 v9, v9
	v_mul_f32_e32 v2, 0xbfb8aa3b, v2
	v_mul_f32_e32 v3, 0xbfb8aa3b, v3
	v_mul_f32_e32 v4, 0xbfb8aa3b, v4
	v_mul_f32_e32 v5, 0xbfb8aa3b, v5
	v_exp_f32_e32 v2, v2
	v_exp_f32_e32 v3, v3
	v_exp_f32_e32 v4, v4
	v_exp_f32_e32 v5, v5
	v_add_f32_e32 v2, 1.0, v2
	v_add_f32_e32 v3, 1.0, v3
	v_add_f32_e32 v4, 1.0, v4
	v_add_f32_e32 v5, 1.0, v5
	v_rcp_f32_e32 v2, v2
	v_rcp_f32_e32 v3, v3
	v_rcp_f32_e32 v4, v4
	v_rcp_f32_e32 v5, v5
	v_cvt_pk_bf16_f32 v14, v14, v15
	v_cvt_pk_bf16_f32 v15, v16, v17
	v_cvt_pk_bf16_f32 v16, v10, v11
	v_cvt_pk_bf16_f32 v17, v12, v13
	v_cvt_pk_bf16_f32 v6, v6, v7
	v_cvt_pk_bf16_f32 v7, v8, v9
	v_cvt_pk_bf16_f32 v8, v2, v3
	v_cvt_pk_bf16_f32 v9, v4, v5
	s_nop 1
	v_permlane16_swap_b32_e32 v14, v16
	v_permlane16_swap_b32_e32 v15, v17
	v_permlane16_swap_b32_e32 v6, v8
	v_permlane16_swap_b32_e32 v7, v9
	global_store_dwordx4 v0, v[14:17], s[14:15]
	global_store_dwordx4 v0, v[6:9], s[14:15] offset:64
	v_mov_b32_e32 v10, 0
	v_mov_b32_e32 v11, 0
	v_mov_b32_e32 v12, 0
	v_mov_b32_e32 v13, 0
	v_mov_b32_e32 v2, 0
	v_mov_b32_e32 v3, 0
	v_mov_b32_e32 v4, 0
	v_mov_b32_e32 v5, 0
	v_mov_b32_e32 v14, 0
	v_mov_b32_e32 v15, 0
	v_mov_b32_e32 v16, 0
	v_mov_b32_e32 v17, 0
	v_mov_b32_e32 v6, 0
	v_mov_b32_e32 v7, 0
	v_mov_b32_e32 v8, 0
	v_mov_b32_e32 v9, 0
	s_branch .Lp2_epi0_done
.Lp2_epi0_plain:
	v_cvt_pk_bf16_f32 v126, v126, v127
	v_cvt_pk_bf16_f32 v127, v128, v129
	v_cvt_pk_bf16_f32 v128, v122, v123
	v_cvt_pk_bf16_f32 v129, v124, v125
	v_cvt_pk_bf16_f32 v118, v118, v119
	v_cvt_pk_bf16_f32 v119, v120, v121
	v_cvt_pk_bf16_f32 v120, v114, v115
	v_cvt_pk_bf16_f32 v121, v116, v117
	s_nop 1
	v_permlane16_swap_b32_e32 v126, v128
	v_permlane16_swap_b32_e32 v127, v129
	v_permlane16_swap_b32_e32 v118, v120
	v_permlane16_swap_b32_e32 v119, v121
	global_store_dwordx4 v0, v[126:129], s[14:15]
	global_store_dwordx4 v0, v[118:121], s[14:15] offset:64
	v_mov_b32_e32 v122, 0
	v_mov_b32_e32 v123, 0
	v_mov_b32_e32 v124, 0
	v_mov_b32_e32 v125, 0
	v_mov_b32_e32 v114, 0
	v_mov_b32_e32 v115, 0
	v_mov_b32_e32 v116, 0
	v_mov_b32_e32 v117, 0
	v_mov_b32_e32 v126, 0
	v_mov_b32_e32 v127, 0
	v_mov_b32_e32 v128, 0
	v_mov_b32_e32 v129, 0
	v_mov_b32_e32 v118, 0
	v_mov_b32_e32 v119, 0
	v_mov_b32_e32 v120, 0
	v_mov_b32_e32 v121, 0
	s_add_u32 s14, s14, 0x78000
	s_addc_u32 s15, s15, 0
	v_cvt_pk_bf16_f32 v110, v110, v111
	v_cvt_pk_bf16_f32 v111, v112, v113
	v_cvt_pk_bf16_f32 v112, v106, v107
	v_cvt_pk_bf16_f32 v113, v108, v109
	v_cvt_pk_bf16_f32 v102, v102, v103
	v_cvt_pk_bf16_f32 v103, v104, v105
	v_cvt_pk_bf16_f32 v104, v98, v99
	v_cvt_pk_bf16_f32 v105, v100, v101
	s_nop 1
	v_permlane16_swap_b32_e32 v110, v112
	v_permlane16_swap_b32_e32 v111, v113
	v_permlane16_swap_b32_e32 v102, v104
	v_permlane16_swap_b32_e32 v103, v105
	global_store_dwordx4 v0, v[110:113], s[14:15]
	global_store_dwordx4 v0, v[102:105], s[14:15] offset:64
	v_mov_b32_e32 v106, 0
	v_mov_b32_e32 v107, 0
	v_mov_b32_e32 v108, 0
	v_mov_b32_e32 v109, 0
	v_mov_b32_e32 v98, 0
	v_mov_b32_e32 v99, 0
	v_mov_b32_e32 v100, 0
	v_mov_b32_e32 v101, 0
	v_mov_b32_e32 v110, 0
	v_mov_b32_e32 v111, 0
	v_mov_b32_e32 v112, 0
	v_mov_b32_e32 v113, 0
	v_mov_b32_e32 v102, 0
	v_mov_b32_e32 v103, 0
	v_mov_b32_e32 v104, 0
	v_mov_b32_e32 v105, 0
	s_add_u32 s14, s14, 0x78000
	s_addc_u32 s15, s15, 0
	v_cvt_pk_bf16_f32 v94, v94, v95
	v_cvt_pk_bf16_f32 v95, v96, v97
	v_cvt_pk_bf16_f32 v96, v90, v91
	v_cvt_pk_bf16_f32 v97, v92, v93
	v_cvt_pk_bf16_f32 v86, v86, v87
	v_cvt_pk_bf16_f32 v87, v88, v89
	v_cvt_pk_bf16_f32 v88, v82, v83
	v_cvt_pk_bf16_f32 v89, v84, v85
	s_nop 1
	v_permlane16_swap_b32_e32 v94, v96
	v_permlane16_swap_b32_e32 v95, v97
	v_permlane16_swap_b32_e32 v86, v88
	v_permlane16_swap_b32_e32 v87, v89
	global_store_dwordx4 v0, v[94:97], s[14:15]
	global_store_dwordx4 v0, v[86:89], s[14:15] offset:64
	v_mov_b32_e32 v90, 0
	v_mov_b32_e32 v91, 0
	v_mov_b32_e32 v92, 0
	v_mov_b32_e32 v93, 0
	v_mov_b32_e32 v82, 0
	v_mov_b32_e32 v83, 0
	v_mov_b32_e32 v84, 0
	v_mov_b32_e32 v85, 0
	v_mov_b32_e32 v94, 0
	v_mov_b32_e32 v95, 0
	v_mov_b32_e32 v96, 0
	v_mov_b32_e32 v97, 0
	v_mov_b32_e32 v86, 0
	v_mov_b32_e32 v87, 0
	v_mov_b32_e32 v88, 0
	v_mov_b32_e32 v89, 0
	s_add_u32 s14, s14, 0x78000
	s_addc_u32 s15, s15, 0
	v_cvt_pk_bf16_f32 v78, v78, v79
	v_cvt_pk_bf16_f32 v79, v80, v81
	v_cvt_pk_bf16_f32 v80, v74, v75
	v_cvt_pk_bf16_f32 v81, v76, v77
	v_cvt_pk_bf16_f32 v70, v70, v71
	v_cvt_pk_bf16_f32 v71, v72, v73
	v_cvt_pk_bf16_f32 v72, v66, v67
	v_cvt_pk_bf16_f32 v73, v68, v69
	s_nop 1
	v_permlane16_swap_b32_e32 v78, v80
	v_permlane16_swap_b32_e32 v79, v81
	v_permlane16_swap_b32_e32 v70, v72
	v_permlane16_swap_b32_e32 v71, v73
	global_store_dwordx4 v0, v[78:81], s[14:15]
	global_store_dwordx4 v0, v[70:73], s[14:15] offset:64
	v_mov_b32_e32 v74, 0
	v_mov_b32_e32 v75, 0
	v_mov_b32_e32 v76, 0
	v_mov_b32_e32 v77, 0
	v_mov_b32_e32 v66, 0
	v_mov_b32_e32 v67, 0
	v_mov_b32_e32 v68, 0
	v_mov_b32_e32 v69, 0
	v_mov_b32_e32 v78, 0
	v_mov_b32_e32 v79, 0
	v_mov_b32_e32 v80, 0
	v_mov_b32_e32 v81, 0
	v_mov_b32_e32 v70, 0
	v_mov_b32_e32 v71, 0
	v_mov_b32_e32 v72, 0
	v_mov_b32_e32 v73, 0
	s_add_u32 s14, s14, 0x78000
	s_addc_u32 s15, s15, 0
	v_cvt_pk_bf16_f32 v62, v62, v63
	v_cvt_pk_bf16_f32 v63, v64, v65
	v_cvt_pk_bf16_f32 v64, v58, v59
	v_cvt_pk_bf16_f32 v65, v60, v61
	v_cvt_pk_bf16_f32 v54, v54, v55
	v_cvt_pk_bf16_f32 v55, v56, v57
	v_cvt_pk_bf16_f32 v56, v50, v51
	v_cvt_pk_bf16_f32 v57, v52, v53
	s_nop 1
	v_permlane16_swap_b32_e32 v62, v64
	v_permlane16_swap_b32_e32 v63, v65
	v_permlane16_swap_b32_e32 v54, v56
	v_permlane16_swap_b32_e32 v55, v57
	global_store_dwordx4 v0, v[62:65], s[14:15]
	global_store_dwordx4 v0, v[54:57], s[14:15] offset:64
	v_mov_b32_e32 v58, 0
	v_mov_b32_e32 v59, 0
	v_mov_b32_e32 v60, 0
	v_mov_b32_e32 v61, 0
	v_mov_b32_e32 v50, 0
	v_mov_b32_e32 v51, 0
	v_mov_b32_e32 v52, 0
	v_mov_b32_e32 v53, 0
	v_mov_b32_e32 v62, 0
	v_mov_b32_e32 v63, 0
	v_mov_b32_e32 v64, 0
	v_mov_b32_e32 v65, 0
	v_mov_b32_e32 v54, 0
	v_mov_b32_e32 v55, 0
	v_mov_b32_e32 v56, 0
	v_mov_b32_e32 v57, 0
	s_add_u32 s14, s14, 0x78000
	s_addc_u32 s15, s15, 0
	v_cvt_pk_bf16_f32 v46, v46, v47
	v_cvt_pk_bf16_f32 v47, v48, v49
	v_cvt_pk_bf16_f32 v48, v42, v43
	v_cvt_pk_bf16_f32 v49, v44, v45
	v_cvt_pk_bf16_f32 v38, v38, v39
	v_cvt_pk_bf16_f32 v39, v40, v41
	v_cvt_pk_bf16_f32 v40, v34, v35
	v_cvt_pk_bf16_f32 v41, v36, v37
	s_nop 1
	v_permlane16_swap_b32_e32 v46, v48
	v_permlane16_swap_b32_e32 v47, v49
	v_permlane16_swap_b32_e32 v38, v40
	v_permlane16_swap_b32_e32 v39, v41
	global_store_dwordx4 v0, v[46:49], s[14:15]
	global_store_dwordx4 v0, v[38:41], s[14:15] offset:64
	v_mov_b32_e32 v42, 0
	v_mov_b32_e32 v43, 0
	v_mov_b32_e32 v44, 0
	v_mov_b32_e32 v45, 0
	v_mov_b32_e32 v34, 0
	v_mov_b32_e32 v35, 0
	v_mov_b32_e32 v36, 0
	v_mov_b32_e32 v37, 0
	v_mov_b32_e32 v46, 0
	v_mov_b32_e32 v47, 0
	v_mov_b32_e32 v48, 0
	v_mov_b32_e32 v49, 0
	v_mov_b32_e32 v38, 0
	v_mov_b32_e32 v39, 0
	v_mov_b32_e32 v40, 0
	v_mov_b32_e32 v41, 0
	s_add_u32 s14, s14, 0x78000
	s_addc_u32 s15, s15, 0
	v_cvt_pk_bf16_f32 v30, v30, v31
	v_cvt_pk_bf16_f32 v31, v32, v33
	v_cvt_pk_bf16_f32 v32, v26, v27
	v_cvt_pk_bf16_f32 v33, v28, v29
	v_cvt_pk_bf16_f32 v22, v22, v23
	v_cvt_pk_bf16_f32 v23, v24, v25
	v_cvt_pk_bf16_f32 v24, v18, v19
	v_cvt_pk_bf16_f32 v25, v20, v21
	s_nop 1
	v_permlane16_swap_b32_e32 v30, v32
	v_permlane16_swap_b32_e32 v31, v33
	v_permlane16_swap_b32_e32 v22, v24
	v_permlane16_swap_b32_e32 v23, v25
	global_store_dwordx4 v0, v[30:33], s[14:15]
	global_store_dwordx4 v0, v[22:25], s[14:15] offset:64
	v_mov_b32_e32 v26, 0
	v_mov_b32_e32 v27, 0
	v_mov_b32_e32 v28, 0
	v_mov_b32_e32 v29, 0
	v_mov_b32_e32 v18, 0
	v_mov_b32_e32 v19, 0
	v_mov_b32_e32 v20, 0
	v_mov_b32_e32 v21, 0
	v_mov_b32_e32 v30, 0
	v_mov_b32_e32 v31, 0
	v_mov_b32_e32 v32, 0
	v_mov_b32_e32 v33, 0
	v_mov_b32_e32 v22, 0
	v_mov_b32_e32 v23, 0
	v_mov_b32_e32 v24, 0
	v_mov_b32_e32 v25, 0
	s_add_u32 s14, s14, 0x78000
	s_addc_u32 s15, s15, 0
	v_cvt_pk_bf16_f32 v14, v14, v15
	v_cvt_pk_bf16_f32 v15, v16, v17
	v_cvt_pk_bf16_f32 v16, v10, v11
	v_cvt_pk_bf16_f32 v17, v12, v13
	v_cvt_pk_bf16_f32 v6, v6, v7
	v_cvt_pk_bf16_f32 v7, v8, v9
	v_cvt_pk_bf16_f32 v8, v2, v3
	v_cvt_pk_bf16_f32 v9, v4, v5
	s_nop 1
	v_permlane16_swap_b32_e32 v14, v16
	v_permlane16_swap_b32_e32 v15, v17
	v_permlane16_swap_b32_e32 v6, v8
	v_permlane16_swap_b32_e32 v7, v9
	global_store_dwordx4 v0, v[14:17], s[14:15]
	global_store_dwordx4 v0, v[6:9], s[14:15] offset:64
	v_mov_b32_e32 v10, 0
	v_mov_b32_e32 v11, 0
	v_mov_b32_e32 v12, 0
	v_mov_b32_e32 v13, 0
	v_mov_b32_e32 v2, 0
	v_mov_b32_e32 v3, 0
	v_mov_b32_e32 v4, 0
	v_mov_b32_e32 v5, 0
	v_mov_b32_e32 v14, 0
	v_mov_b32_e32 v15, 0
	v_mov_b32_e32 v16, 0
	v_mov_b32_e32 v17, 0
	v_mov_b32_e32 v6, 0
	v_mov_b32_e32 v7, 0
	v_mov_b32_e32 v8, 0
	v_mov_b32_e32 v9, 0
.Lp2_epi0_done:
	s_add_i32 s44, s44, 1
	s_mov_b32 s6, 0
	v_add_u32_e32 v0, v158, v159
	v_add_u32_e32 v177, v146, v160
	s_mov_b32 s47, 1
	s_branch .Lp2_cont0

.Lp2_epi1_done:
	s_add_i32 s44, s44, 1
	s_mov_b32 s6, 0
	v_add_u32_e32 v0, v161, v157
	s_mov_b32 s47, 1
	s_branch .Lp2_cont1
.Lp2_wepi0:
	s_mov_b32 s47, 0
	s_waitcnt vmcnt(16) lgkmcnt(0)
	s_branch .Lp2_wjoin0
